# prologue: nt hint also on the write-once bf16 weight / x stores
# baseline (speedup 1.0000x reference)
; #define LAS __attribute__((address_space(3)))
; #define LDS_WAIT() asm volatile("s_waitcnt lgkmcnt(0)" ::: "memory")
; __device__ __forceinline__ unsigned pk2(float lo, float hi) { return pg8::cvt_pk_bf16(lo, hi); }
; __device__ __forceinline__ void transpose_item(const float* W, int K, int N, bf16_t* WT, int mode, const float* kscale, LAS float* scr, int item, int lane) {
;     ...
;     for (int i = 0; i < 8; ++i) { const int kk = 8 * i + (lane >> 3); const float sc = kscale ? kscale[k0 + kk] : 1.f; LAS float* d = scr + kk * 33 + 4 * (lane & 7);
;         d[0] = t[i][0] * sc; d[1] = t[i][1] * sc; d[2] = t[i][2] * sc; d[3] = t[i][3] * sc; }
;     LDS_WAIT(); asm volatile("" ::: "memory");
;     const int c = lane & 7;
; #pragma unroll
;     for (int j = 0; j < 4; ++j) { const int n = (lane >> 3) + 8 * j; const LAS float* s = scr + (8 * c) * 33 + n;
;         int dn = n;
;         if (mode == 3 && n0 >= 2048 && n0 < 6144) { const int d = (n0 & 127) + n; dn = ((d >> 4) & 3) * 32 + ((d >> 2) & 3) * 8 + (d >> 6) * 4 + (d & 3) - (n0 & 127); }
;         u32x4 o; o.x = pk2(s[0 * 33], s[1 * 33]); o.y = pk2(s[2 * 33], s[3 * 33]); o.z = pk2(s[4 * 33], s[5 * 33]); o.w = pk2(s[6 * 33], s[7 * 33]);
;         *(u32x4*)(WT + (size_t)(drow + dn) * K + k0 + 8 * c) = o; }
;     LDS_WAIT(); asm volatile("" ::: "memory");
; }
.LBB0_519:
	v_add_u32_e32 v11, 0x840, v19
	ds_write2_b32 v11, v6, v7 offset1:1
	v_add_u32_e32 v6, 0x848, v19
	ds_write2_b32 v6, v8, v9 offset1:1
	s_waitcnt vmcnt(0)
	v_pk_mul_f32 v[2:3], v[2:3], v[10:11] op_sel_hi:[1,0]
	v_add_u32_e32 v6, 0xc60, v19
	ds_write2_b32 v6, v2, v3 offset1:1
	v_pk_mul_f32 v[2:3], v[4:5], v[10:11] op_sel_hi:[1,0]
	v_add_u32_e32 v4, 0xc68, v19
	ds_write2_b32 v4, v2, v3 offset1:1
	s_waitcnt lgkmcnt(0)
	s_sub_i32 s6, s30, 64
	s_cmpk_lt_u32 s6, 0x80
	ds_read2_b32 v[2:3], v48 offset1:33
	s_cselect_b64 vcc, -1, 0
	s_and_b32 s6, s10, 0x60
	s_lshr_b32 s7, s10, 4
	s_waitcnt lgkmcnt(0)
	v_cvt_pk_bf16_f32 v2, v2, v3
	v_subrev_u32_e32 v3, s6, v50
	v_and_or_b32 v12, s7, 4, v3
	s_lshl_b64 s[6:7], s[18:19], 1
	s_add_u32 s6, s29, s6
	s_addc_u32 s7, s28, s7
	v_lshlrev_b32_e32 v196, 1, v38
	ds_read2_b32 v[4:5], v48 offset0:66 offset1:99
	v_lshl_add_u64 v[6:7], s[6:7], 0, v[196:197]
	s_lshl_b32 s6, s30, 6
	s_waitcnt lgkmcnt(0)
	v_cvt_pk_bf16_f32 v3, v4, v5
	ds_read2_b32 v[4:5], v48 offset0:132 offset1:165
	s_and_b32 s6, s6, 64
	s_waitcnt lgkmcnt(0)
	v_cvt_pk_bf16_f32 v4, v4, v5
	v_or_b32_e32 v5, s6, v51
	v_add_u32_e32 v13, v5, v12
	ds_read2_b32 v[8:9], v48 offset0:198 offset1:231
	v_cndmask_b32_e32 v10, v34, v13, vcc
	s_waitcnt lgkmcnt(0)
	v_cvt_pk_bf16_f32 v5, v8, v9
	v_add_u32_e32 v8, s10, v10
	v_ashrrev_i32_e32 v9, 31, v8
	v_lshlrev_b64 v[8:9], 12, v[8:9]
	v_lshl_add_u64 v[8:9], v[6:7], 0, v[8:9]
	ds_read2_b32 v[10:11], v48 offset0:8 offset1:41
	global_store_dwordx4 v[8:9], v[2:5], off nt
	s_waitcnt lgkmcnt(0)
	s_nop 0
	v_cvt_pk_bf16_f32 v2, v10, v11
	ds_read2_b32 v[4:5], v48 offset0:74 offset1:107
	s_waitcnt lgkmcnt(0)
	v_cvt_pk_bf16_f32 v3, v4, v5
	ds_read2_b32 v[4:5], v48 offset0:140 offset1:173
	s_waitcnt lgkmcnt(0)
	v_cvt_pk_bf16_f32 v4, v4, v5
	v_or_b32_e32 v5, s6, v52
	v_add_u32_e32 v5, v5, v12
	ds_read2_b32 v[8:9], v48 offset0:206 offset1:239
	v_cndmask_b32_e32 v10, v45, v5, vcc
	s_waitcnt lgkmcnt(0)
	v_cvt_pk_bf16_f32 v5, v8, v9
	v_add_u32_e32 v8, s10, v10
	v_ashrrev_i32_e32 v9, 31, v8
	v_lshlrev_b64 v[8:9], 12, v[8:9]
	v_lshl_add_u64 v[8:9], v[6:7], 0, v[8:9]
	ds_read2_b32 v[10:11], v48 offset0:16 offset1:49
	global_store_dwordx4 v[8:9], v[2:5], off nt
	s_waitcnt lgkmcnt(0)
	s_nop 0
	v_cvt_pk_bf16_f32 v2, v10, v11
	ds_read2_b32 v[4:5], v48 offset0:82 offset1:115
	s_waitcnt lgkmcnt(0)
	v_cvt_pk_bf16_f32 v3, v4, v5
	ds_read2_b32 v[4:5], v48 offset0:148 offset1:181
	s_waitcnt lgkmcnt(0)
	v_cvt_pk_bf16_f32 v4, v4, v5
	v_add_u32_e32 v5, 32, v13
	ds_read2_b32 v[8:9], v48 offset0:214 offset1:247
	v_cndmask_b32_e32 v10, v46, v5, vcc
	s_waitcnt lgkmcnt(0)
	v_cvt_pk_bf16_f32 v5, v8, v9
	v_add_u32_e32 v8, s10, v10
	v_ashrrev_i32_e32 v9, 31, v8
	v_lshlrev_b64 v[8:9], 12, v[8:9]
	v_lshl_add_u64 v[8:9], v[6:7], 0, v[8:9]
	ds_read2_b32 v[10:11], v48 offset0:24 offset1:57
	global_store_dwordx4 v[8:9], v[2:5], off nt
	s_waitcnt lgkmcnt(0)
	s_nop 0
	v_cvt_pk_bf16_f32 v2, v10, v11
	ds_read2_b32 v[4:5], v48 offset0:90 offset1:123
	s_waitcnt lgkmcnt(0)
	v_cvt_pk_bf16_f32 v3, v4, v5
	ds_read2_b32 v[4:5], v48 offset0:156 offset1:189
	s_waitcnt lgkmcnt(0)
	v_cvt_pk_bf16_f32 v4, v4, v5
	v_or_b32_e32 v5, s6, v53
	v_add_u32_e32 v5, v5, v12
	v_cndmask_b32_e32 v5, v47, v5, vcc
	v_add_u32_e32 v10, s10, v5
	ds_read2_b32 v[8:9], v48 offset0:222 offset1:255
	v_ashrrev_i32_e32 v11, 31, v10
	s_waitcnt lgkmcnt(0)
	v_cvt_pk_bf16_f32 v5, v8, v9
	v_lshlrev_b64 v[8:9], 12, v[10:11]
	v_lshl_add_u64 v[6:7], v[6:7], 0, v[8:9]
	global_store_dwordx4 v[6:7], v[2:5], off nt
	s_waitcnt lgkmcnt(0)

; #define LAS __attribute__((address_space(3)))
; #define LDS_WAIT() asm volatile("s_waitcnt lgkmcnt(0)" ::: "memory")
; __device__ __forceinline__ unsigned pk2(float lo, float hi) { return pg8::cvt_pk_bf16(lo, hi); }
; __device__ __forceinline__ void transpose_item(const float* W, int K, int N, bf16_t* WT, int mode, const float* kscale, LAS float* scr, int item, int lane) {
;     const int nblk = N / 32, kb = item / nblk, nb = item % nblk, k0 = 64 * kb, n0 = 32 * nb;
;     const int drow = (mode == 0 || mode == 3) ? n0 : ((n0 >> 7) * 256 + (n0 & 127) + (mode == 2 ? 128 : 0));
;     f32x4 t[8];
; #pragma unroll
;     for (int i = 0; i < 8; ++i) t[i] = *(const f32x4*)(W + (size_t)(k0 + 8 * i + (lane >> 3)) * N + n0 + 4 * (lane & 7));
; #pragma unroll
;     for (int i = 0; i < 8; ++i) { const int kk = 8 * i + (lane >> 3); const float sc = kscale ? kscale[k0 + kk] : 1.f; LAS float* d = scr + kk * 33 + 4 * (lane & 7);
;         d[0] = t[i][0] * sc; d[1] = t[i][1] * sc; d[2] = t[i][2] * sc; d[3] = t[i][3] * sc; }
;     LDS_WAIT(); asm volatile("" ::: "memory");
;     const int c = lane & 7;
; #pragma unroll
;     for (int j = 0; j < 4; ++j) { const int n = (lane >> 3) + 8 * j; const LAS float* s = scr + (8 * c) * 33 + n;
;         int dn = n;
;         if (mode == 3 && n0 >= 2048 && n0 < 6144) { const int d = (n0 & 127) + n; dn = ((d >> 4) & 3) * 32 + ((d >> 2) & 3) * 8 + (d >> 6) * 4 + (d & 3) - (n0 & 127); }
;         u32x4 o; o.x = pk2(s[0 * 33], s[1 * 33]); o.y = pk2(s[2 * 33], s[3 * 33]); o.z = pk2(s[4 * 33], s[5 * 33]); o.w = pk2(s[6 * 33], s[7 * 33]);
;         *(u32x4*)(WT + (size_t)(drow + dn) * K + k0 + 8 * c) = o; }
;     LDS_WAIT(); asm volatile("" ::: "memory");
; }
.LBB0_521:
	s_mul_hi_i32 s6, s27, 0xa0a0a0a1
	s_add_i32 s6, s6, s27
	s_lshr_b32 s7, s6, 31
	s_ashr_i32 s6, s6, 14
	s_add_i32 s18, s6, s7
	s_mul_i32 s6, s18, 0xffff9a00
	s_add_i32 s22, s27, s6
	s_ashr_i32 s19, s18, 31
	s_mul_i32 s7, s18, 0x6600000
	s_mul_hi_i32 s6, s18, 0x6600000
	s_add_u32 s29, s15, s7
	s_addc_u32 s28, s24, s6
	s_cmpk_gt_i32 s22, 0x1bff
	s_mov_b64 s[6:7], -1
	s_cbranch_scc0 .LBB0_551
	s_cmpk_gt_u32 s22, 0x23ff
	s_cbranch_scc0 .LBB0_548
	s_cmpk_gt_u32 s22, 0x39ff
	s_mul_hi_i32 s20, s18, 0x2c00000
	s_mul_i32 s21, s18, 0x2c00000
	s_cbranch_scc0 .LBB0_537
	s_cmpk_gt_u32 s22, 0x4fff
	s_cbranch_scc0 .LBB0_526
	s_load_dwordx2 s[6:7], s[16:17], 0x78
	v_lshlrev_b32_e32 v196, 2, v36
	v_mov_b32_e32 v31, v197
	v_add_u32_e32 v40, v39, v41
	v_add_u32_e32 v42, 0x420, v40
	s_waitcnt lgkmcnt(0)
	s_add_u32 s8, s6, s21
	s_addc_u32 s7, s7, s20
	s_and_b32 s9, s22, 0x7fffffc0
	s_and_b32 s6, s25, 0x7e0
	s_add_i32 s86, s9, 0xffffb000
	s_lshl_b32 s9, s6, 2
	s_add_u32 s8, s8, s9
	v_or_b32_e32 v30, s86, v34
	s_addc_u32 s9, s7, 0
	v_lshl_add_u64 v[32:33], s[8:9], 0, v[196:197]
	v_or_b32_e32 v196, 8, v30
	v_lshlrev_b64 v[4:5], 13, v[196:197]
	v_or_b32_e32 v196, 16, v30
	v_lshlrev_b64 v[10:11], 13, v[196:197]
	v_or_b32_e32 v196, 24, v30
	v_lshlrev_b64 v[12:13], 13, v[196:197]
	v_or_b32_e32 v196, 32, v30
	v_lshlrev_b64 v[18:19], 13, v[196:197]
	v_or_b32_e32 v196, 40, v30
	v_lshlrev_b64 v[2:3], 13, v[30:31]
	v_lshlrev_b64 v[20:21], 13, v[196:197]
	v_lshl_add_u64 v[2:3], v[32:33], 0, v[2:3]
	v_lshl_add_u64 v[6:7], v[32:33], 0, v[4:5]
	v_lshl_add_u64 v[10:11], v[32:33], 0, v[10:11]
	v_lshl_add_u64 v[14:15], v[32:33], 0, v[12:13]
	v_lshl_add_u64 v[18:19], v[32:33], 0, v[18:19]
	v_lshl_add_u64 v[22:23], v[32:33], 0, v[20:21]
	global_load_dwordx4 v[2:5], v[2:3], off nt
	s_nop 0
	global_load_dwordx4 v[6:9], v[6:7], off nt
	s_nop 0
	global_load_dwordx4 v[10:13], v[10:11], off nt
	s_nop 0
	global_load_dwordx4 v[14:17], v[14:15], off nt
	s_nop 0
	global_load_dwordx4 v[18:21], v[18:19], off nt
	s_nop 0
	global_load_dwordx4 v[22:25], v[22:23], off nt
	v_or_b32_e32 v196, 48, v30
	v_lshlrev_b64 v[26:27], 13, v[196:197]
	v_lshl_add_u64 v[26:27], v[32:33], 0, v[26:27]
	v_or_b32_e32 v196, 56, v30
	global_load_dwordx4 v[26:29], v[26:27], off nt
	v_lshlrev_b64 v[30:31], 13, v[196:197]
	v_lshl_add_u64 v[30:31], v[32:33], 0, v[30:31]
	global_load_dwordx4 v[30:33], v[30:31], off nt
	v_add_u32_e32 v43, 0x428, v40
	v_add_u32_e32 v44, 0x840, v40
	v_add_u32_e32 v54, 0x848, v40
	v_add_u32_e32 v55, 0xc60, v40
	v_add_u32_e32 v56, 0xc68, v40
	v_add_u32_e32 v57, 0x1080, v40
	v_add_u32_e32 v58, 0x1088, v40
	v_add_u32_e32 v59, 0x14a0, v40
	v_add_u32_e32 v60, 0x14a8, v40
	v_add_u32_e32 v61, 0x18c0, v40
	v_add_u32_e32 v62, 0x18c8, v40
	v_add_u32_e32 v63, 0x1ce0, v40
	v_add_u32_e32 v64, 0x1ce8, v40
	s_lshl_b64 s[8:9], s[86:87], 1
	s_add_u32 s8, s29, s8
	s_addc_u32 s9, s28, s9
	v_lshlrev_b32_e32 v196, 1, v38
	s_mov_b32 s86, 0x80000
	s_waitcnt vmcnt(0)
	ds_write2_b32 v40, v2, v3 offset1:1
	ds_write2_b32 v40, v4, v5 offset0:2 offset1:3
	ds_write2_b32 v42, v6, v7 offset1:1
	ds_write2_b32 v43, v8, v9 offset1:1
	ds_write2_b32 v44, v10, v11 offset1:1
	ds_write2_b32 v54, v12, v13 offset1:1
	ds_write2_b32 v55, v14, v15 offset1:1
	ds_write2_b32 v56, v16, v17 offset1:1
	ds_write2_b32 v57, v18, v19 offset1:1
	ds_write2_b32 v58, v20, v21 offset1:1
	ds_write2_b32 v59, v22, v23 offset1:1
	ds_write2_b32 v60, v24, v25 offset1:1
	ds_write2_b32 v61, v26, v27 offset1:1
	ds_write2_b32 v62, v28, v29 offset1:1
	ds_write2_b32 v63, v30, v31 offset1:1
	ds_write2_b32 v64, v32, v33 offset1:1
	s_waitcnt lgkmcnt(0)
	v_or_b32_e32 v6, s6, v34
	ds_read2_b32 v[2:3], v48 offset1:33
	v_mul_u32_u24_e32 v10, 0x1600, v6
	v_lshl_add_u64 v[8:9], s[8:9], 0, v[196:197]
	s_mov_b64 s[8:9], 0x5000000
	s_waitcnt lgkmcnt(0)
	v_cvt_pk_bf16_f32 v2, v2, v3
	ds_read2_b32 v[4:5], v48 offset0:66 offset1:99
	v_lshlrev_b32_e32 v196, 1, v10
	v_lshl_add_u64 v[8:9], v[8:9], 0, s[8:9]
	s_waitcnt lgkmcnt(0)
	v_cvt_pk_bf16_f32 v3, v4, v5
	ds_read2_b32 v[4:5], v48 offset0:132 offset1:165
	v_lshl_add_u64 v[10:11], v[8:9], 0, v[196:197]
	s_waitcnt lgkmcnt(0)
	v_cvt_pk_bf16_f32 v4, v4, v5
	ds_read2_b32 v[6:7], v48 offset0:198 offset1:231
	s_waitcnt lgkmcnt(0)
	v_cvt_pk_bf16_f32 v5, v6, v7
	global_store_dwordx4 v[10:11], v[2:5], off nt
	v_or_b32_e32 v10, s6, v45
	v_mul_u32_u24_e32 v10, 0x1600, v10
	ds_read2_b32 v[6:7], v48 offset0:8 offset1:41
	s_waitcnt lgkmcnt(0)
	v_cvt_pk_bf16_f32 v2, v6, v7
	ds_read2_b32 v[4:5], v48 offset0:74 offset1:107
	v_lshlrev_b32_e32 v196, 1, v10
	s_waitcnt lgkmcnt(0)
	v_cvt_pk_bf16_f32 v3, v4, v5
	ds_read2_b32 v[4:5], v48 offset0:140 offset1:173
	v_lshl_add_u64 v[10:11], v[8:9], 0, v[196:197]
	s_waitcnt lgkmcnt(0)
	v_cvt_pk_bf16_f32 v4, v4, v5
	ds_read2_b32 v[6:7], v48 offset0:206 offset1:239
	s_waitcnt lgkmcnt(0)
	v_cvt_pk_bf16_f32 v5, v6, v7
	global_store_dwordx4 v[10:11], v[2:5], off nt
	v_or_b32_e32 v10, s6, v46
	ds_read2_b32 v[6:7], v48 offset0:16 offset1:49
	s_waitcnt lgkmcnt(0)
	v_cvt_pk_bf16_f32 v2, v6, v7
	ds_read2_b32 v[4:5], v48 offset0:82 offset1:115
	v_mul_u32_u24_e32 v10, 0x1600, v10
	s_waitcnt lgkmcnt(0)
	v_cvt_pk_bf16_f32 v3, v4, v5
	ds_read2_b32 v[4:5], v48 offset0:148 offset1:181
	v_lshlrev_b32_e32 v196, 1, v10
	s_waitcnt lgkmcnt(0)
	v_cvt_pk_bf16_f32 v4, v4, v5
	ds_read2_b32 v[6:7], v48 offset0:214 offset1:247
	s_waitcnt lgkmcnt(0)
	v_cvt_pk_bf16_f32 v5, v6, v7
	v_lshl_add_u64 v[10:11], v[8:9], 0, v[196:197]
	ds_read2_b32 v[6:7], v48 offset0:24 offset1:57
	global_store_dwordx4 v[10:11], v[2:5], off nt
	s_waitcnt lgkmcnt(0)
	s_nop 0
	v_cvt_pk_bf16_f32 v2, v6, v7
	ds_read2_b32 v[4:5], v48 offset0:90 offset1:123
	s_waitcnt lgkmcnt(0)
	v_cvt_pk_bf16_f32 v3, v4, v5
	ds_read2_b32 v[4:5], v48 offset0:156 offset1:189
	s_waitcnt lgkmcnt(0)
	v_cvt_pk_bf16_f32 v4, v4, v5
	v_or_b32_e32 v5, s6, v47
	v_mul_u32_u24_e32 v5, 0x1600, v5
	ds_read2_b32 v[6:7], v48 offset0:222 offset1:255
	v_lshlrev_b32_e32 v196, 1, v5
	s_waitcnt lgkmcnt(0)
	v_cvt_pk_bf16_f32 v5, v6, v7
	v_lshl_add_u64 v[6:7], v[8:9], 0, v[196:197]
	global_store_dwordx4 v[6:7], v[2:5], off nt
	s_waitcnt lgkmcnt(0)
	s_mov_b64 s[6:7], 0

; #define LAS __attribute__((address_space(3)))
; #define LDS_WAIT() asm volatile("s_waitcnt lgkmcnt(0)" ::: "memory")
; __device__ __forceinline__ unsigned pk2(float lo, float hi) { return pg8::cvt_pk_bf16(lo, hi); }
; __device__ __forceinline__ void transpose_item(const float* W, int K, int N, bf16_t* WT, int mode, const float* kscale, LAS float* scr, int item, int lane) {
;     ...
;     for (int i = 0; i < 8; ++i) { const int kk = 8 * i + (lane >> 3); const float sc = kscale ? kscale[k0 + kk] : 1.f; LAS float* d = scr + kk * 33 + 4 * (lane & 7);
;         d[0] = t[i][0] * sc; d[1] = t[i][1] * sc; d[2] = t[i][2] * sc; d[3] = t[i][3] * sc; }
;     LDS_WAIT(); asm volatile("" ::: "memory");
;     const int c = lane & 7;
; #pragma unroll
;     for (int j = 0; j < 4; ++j) { const int n = (lane >> 3) + 8 * j; const LAS float* s = scr + (8 * c) * 33 + n;
;         int dn = n;
;         if (mode == 3 && n0 >= 2048 && n0 < 6144) { const int d = (n0 & 127) + n; dn = ((d >> 4) & 3) * 32 + ((d >> 2) & 3) * 8 + (d >> 6) * 4 + (d & 3) - (n0 & 127); }
;         u32x4 o; o.x = pk2(s[0 * 33], s[1 * 33]); o.y = pk2(s[2 * 33], s[3 * 33]); o.z = pk2(s[4 * 33], s[5 * 33]); o.w = pk2(s[6 * 33], s[7 * 33]);
;         *(u32x4*)(WT + (size_t)(drow + dn) * K + k0 + 8 * c) = o; }
;     LDS_WAIT(); asm volatile("" ::: "memory");
; }
.LBB0_535:
	v_add_u32_e32 v10, 0x840, v19
	ds_write2_b32 v10, v6, v7 offset1:1
	v_add_u32_e32 v6, 0x848, v19
	ds_write2_b32 v6, v8, v9 offset1:1
	s_waitcnt vmcnt(0)
	v_pk_mul_f32 v[2:3], v[2:3], v[18:19] op_sel_hi:[1,0]
	v_add_u32_e32 v6, 0xc60, v19
	s_lshl_b32 s6, s30, 5
	s_lshl_b32 s7, s30, 6
	ds_write2_b32 v6, v2, v3 offset1:1
	v_pk_mul_f32 v[2:3], v[4:5], v[18:19] op_sel_hi:[1,0]
	v_add_u32_e32 v4, 0xc68, v19
	s_and_b32 s7, s7, 0x3f00
	s_and_b32 s6, s6, 0x60
	ds_write2_b32 v4, v2, v3 offset1:1
	s_or_b32 s6, s7, s6
	s_waitcnt lgkmcnt(0)
	s_or_b32 s8, s6, 0x80
	s_lshl_b32 s6, s23, 1
	s_add_u32 s6, s29, s6
	ds_read2_b32 v[2:3], v48 offset1:33
	s_addc_u32 s7, s28, 0
	v_lshlrev_b32_e32 v196, 1, v38
	s_waitcnt lgkmcnt(0)
	v_cvt_pk_bf16_f32 v2, v2, v3
	ds_read2_b32 v[4:5], v48 offset0:66 offset1:99
	v_lshl_add_u64 v[8:9], s[6:7], 0, v[196:197]
	s_mov_b64 s[6:7], 0x2400000
	v_or_b32_e32 v10, s8, v34
	s_waitcnt lgkmcnt(0)
	v_cvt_pk_bf16_f32 v3, v4, v5
	ds_read2_b32 v[4:5], v48 offset0:132 offset1:165
	v_lshl_add_u64 v[8:9], v[8:9], 0, s[6:7]
	v_lshlrev_b32_e32 v196, 12, v10
	s_waitcnt lgkmcnt(0)
	v_cvt_pk_bf16_f32 v4, v4, v5
	ds_read2_b32 v[6:7], v48 offset0:198 offset1:231
	s_waitcnt lgkmcnt(0)
	v_cvt_pk_bf16_f32 v5, v6, v7
	v_lshl_add_u64 v[10:11], v[8:9], 0, v[196:197]
	ds_read2_b32 v[6:7], v48 offset0:8 offset1:41
	global_store_dwordx4 v[10:11], v[2:5], off nt
	v_or_b32_e32 v10, s8, v45
	v_lshlrev_b32_e32 v196, 12, v10
	s_waitcnt lgkmcnt(0)
	v_cvt_pk_bf16_f32 v2, v6, v7
	ds_read2_b32 v[4:5], v48 offset0:74 offset1:107
	s_waitcnt lgkmcnt(0)
	v_cvt_pk_bf16_f32 v3, v4, v5
	ds_read2_b32 v[4:5], v48 offset0:140 offset1:173
	s_waitcnt lgkmcnt(0)
	v_cvt_pk_bf16_f32 v4, v4, v5
	ds_read2_b32 v[6:7], v48 offset0:206 offset1:239
	s_waitcnt lgkmcnt(0)
	v_cvt_pk_bf16_f32 v5, v6, v7
	v_lshl_add_u64 v[10:11], v[8:9], 0, v[196:197]
	ds_read2_b32 v[6:7], v48 offset0:16 offset1:49
	global_store_dwordx4 v[10:11], v[2:5], off nt
	v_or_b32_e32 v10, s8, v46
	v_lshlrev_b32_e32 v196, 12, v10
	s_waitcnt lgkmcnt(0)
	v_cvt_pk_bf16_f32 v2, v6, v7
	ds_read2_b32 v[4:5], v48 offset0:82 offset1:115
	s_waitcnt lgkmcnt(0)
	v_cvt_pk_bf16_f32 v3, v4, v5
	ds_read2_b32 v[4:5], v48 offset0:148 offset1:181
	s_waitcnt lgkmcnt(0)
	v_cvt_pk_bf16_f32 v4, v4, v5
	ds_read2_b32 v[6:7], v48 offset0:214 offset1:247
	s_waitcnt lgkmcnt(0)
	v_cvt_pk_bf16_f32 v5, v6, v7
	v_lshl_add_u64 v[10:11], v[8:9], 0, v[196:197]
	ds_read2_b32 v[6:7], v48 offset0:24 offset1:57
	global_store_dwordx4 v[10:11], v[2:5], off nt
	s_waitcnt lgkmcnt(0)
	s_nop 0
	v_cvt_pk_bf16_f32 v2, v6, v7
	ds_read2_b32 v[4:5], v48 offset0:90 offset1:123
	s_waitcnt lgkmcnt(0)
	v_cvt_pk_bf16_f32 v3, v4, v5
	ds_read2_b32 v[4:5], v48 offset0:156 offset1:189
	s_waitcnt lgkmcnt(0)
	v_cvt_pk_bf16_f32 v4, v4, v5
	v_or_b32_e32 v5, s8, v47
	ds_read2_b32 v[6:7], v48 offset0:222 offset1:255
	v_lshlrev_b32_e32 v196, 12, v5
	s_waitcnt lgkmcnt(0)
	v_cvt_pk_bf16_f32 v5, v6, v7
	v_lshl_add_u64 v[6:7], v[8:9], 0, v[196:197]
	global_store_dwordx4 v[6:7], v[2:5], off nt
	s_waitcnt lgkmcnt(0)

; #define LAS __attribute__((address_space(3)))
; #define LDS_WAIT() asm volatile("s_waitcnt lgkmcnt(0)" ::: "memory")
; __device__ __forceinline__ unsigned pk2(float lo, float hi) { return pg8::cvt_pk_bf16(lo, hi); }
; __device__ __forceinline__ void transpose_item(const float* W, int K, int N, bf16_t* WT, int mode, const float* kscale, LAS float* scr, int item, int lane) {
;     ...
;     for (int i = 0; i < 8; ++i) { const int kk = 8 * i + (lane >> 3); const float sc = kscale ? kscale[k0 + kk] : 1.f; LAS float* d = scr + kk * 33 + 4 * (lane & 7);
;         d[0] = t[i][0] * sc; d[1] = t[i][1] * sc; d[2] = t[i][2] * sc; d[3] = t[i][3] * sc; }
;     LDS_WAIT(); asm volatile("" ::: "memory");
;     const int c = lane & 7;
; #pragma unroll
;     for (int j = 0; j < 4; ++j) { const int n = (lane >> 3) + 8 * j; const LAS float* s = scr + (8 * c) * 33 + n;
;         int dn = n;
;         if (mode == 3 && n0 >= 2048 && n0 < 6144) { const int d = (n0 & 127) + n; dn = ((d >> 4) & 3) * 32 + ((d >> 2) & 3) * 8 + (d >> 6) * 4 + (d & 3) - (n0 & 127); }
;         u32x4 o; o.x = pk2(s[0 * 33], s[1 * 33]); o.y = pk2(s[2 * 33], s[3 * 33]); o.z = pk2(s[4 * 33], s[5 * 33]); o.w = pk2(s[6 * 33], s[7 * 33]);
;         *(u32x4*)(WT + (size_t)(drow + dn) * K + k0 + 8 * c) = o; }
;     LDS_WAIT(); asm volatile("" ::: "memory");
; }
.LBB0_546:
	v_add_u32_e32 v10, 0x840, v19
	ds_write2_b32 v10, v6, v7 offset1:1
	v_add_u32_e32 v6, 0x848, v19
	ds_write2_b32 v6, v8, v9 offset1:1
	s_waitcnt vmcnt(0)
	v_pk_mul_f32 v[2:3], v[2:3], v[18:19] op_sel_hi:[1,0]
	v_add_u32_e32 v6, 0xc60, v19
	ds_write2_b32 v6, v2, v3 offset1:1
	v_pk_mul_f32 v[2:3], v[4:5], v[18:19] op_sel_hi:[1,0]
	v_add_u32_e32 v4, 0xc68, v19
	s_lshl_b32 s6, s30, 5
	s_lshl_b32 s7, s30, 6
	ds_write2_b32 v4, v2, v3 offset1:1
	s_and_b32 s7, s7, 0x3f00
	s_and_b32 s6, s6, 0x60
	s_waitcnt lgkmcnt(0)
	s_or_b32 s8, s6, s7
	s_lshl_b32 s6, s23, 1
	s_add_u32 s6, s29, s6
	ds_read2_b32 v[2:3], v48 offset1:33
	s_addc_u32 s7, s28, 0
	v_lshlrev_b32_e32 v196, 1, v38
	s_waitcnt lgkmcnt(0)
	v_cvt_pk_bf16_f32 v2, v2, v3
	ds_read2_b32 v[4:5], v48 offset0:66 offset1:99
	v_lshl_add_u64 v[8:9], s[6:7], 0, v[196:197]
	s_mov_b64 s[6:7], 0x2400000
	v_or_b32_e32 v10, s8, v34
	s_waitcnt lgkmcnt(0)
	v_cvt_pk_bf16_f32 v3, v4, v5
	ds_read2_b32 v[4:5], v48 offset0:132 offset1:165
	v_lshl_add_u64 v[8:9], v[8:9], 0, s[6:7]
	v_lshlrev_b32_e32 v196, 12, v10
	s_waitcnt lgkmcnt(0)
	v_cvt_pk_bf16_f32 v4, v4, v5
	ds_read2_b32 v[6:7], v48 offset0:198 offset1:231
	s_waitcnt lgkmcnt(0)
	v_cvt_pk_bf16_f32 v5, v6, v7
	v_lshl_add_u64 v[10:11], v[8:9], 0, v[196:197]
	ds_read2_b32 v[6:7], v48 offset0:8 offset1:41
	global_store_dwordx4 v[10:11], v[2:5], off nt
	v_or_b32_e32 v10, s8, v45
	v_lshlrev_b32_e32 v196, 12, v10
	s_waitcnt lgkmcnt(0)
	v_cvt_pk_bf16_f32 v2, v6, v7
	ds_read2_b32 v[4:5], v48 offset0:74 offset1:107
	s_waitcnt lgkmcnt(0)
	v_cvt_pk_bf16_f32 v3, v4, v5
	ds_read2_b32 v[4:5], v48 offset0:140 offset1:173
	s_waitcnt lgkmcnt(0)
	v_cvt_pk_bf16_f32 v4, v4, v5
	ds_read2_b32 v[6:7], v48 offset0:206 offset1:239
	s_waitcnt lgkmcnt(0)
	v_cvt_pk_bf16_f32 v5, v6, v7
	v_lshl_add_u64 v[10:11], v[8:9], 0, v[196:197]
	ds_read2_b32 v[6:7], v48 offset0:16 offset1:49
	global_store_dwordx4 v[10:11], v[2:5], off nt
	v_or_b32_e32 v10, s8, v46
	v_lshlrev_b32_e32 v196, 12, v10
	s_waitcnt lgkmcnt(0)
	v_cvt_pk_bf16_f32 v2, v6, v7
	ds_read2_b32 v[4:5], v48 offset0:82 offset1:115
	s_waitcnt lgkmcnt(0)
	v_cvt_pk_bf16_f32 v3, v4, v5
	ds_read2_b32 v[4:5], v48 offset0:148 offset1:181
	s_waitcnt lgkmcnt(0)
	v_cvt_pk_bf16_f32 v4, v4, v5
	ds_read2_b32 v[6:7], v48 offset0:214 offset1:247
	s_waitcnt lgkmcnt(0)
	v_cvt_pk_bf16_f32 v5, v6, v7
	v_lshl_add_u64 v[10:11], v[8:9], 0, v[196:197]
	ds_read2_b32 v[6:7], v48 offset0:24 offset1:57
	global_store_dwordx4 v[10:11], v[2:5], off nt
	s_waitcnt lgkmcnt(0)
	s_nop 0
	v_cvt_pk_bf16_f32 v2, v6, v7
	ds_read2_b32 v[4:5], v48 offset0:90 offset1:123
	s_waitcnt lgkmcnt(0)
	v_cvt_pk_bf16_f32 v3, v4, v5
	ds_read2_b32 v[4:5], v48 offset0:156 offset1:189
	s_waitcnt lgkmcnt(0)
	v_cvt_pk_bf16_f32 v4, v4, v5
	v_or_b32_e32 v5, s8, v47
	ds_read2_b32 v[6:7], v48 offset0:222 offset1:255
	v_lshlrev_b32_e32 v196, 12, v5
	s_waitcnt lgkmcnt(0)
	v_cvt_pk_bf16_f32 v5, v6, v7
	v_lshl_add_u64 v[6:7], v[8:9], 0, v[196:197]
	global_store_dwordx4 v[6:7], v[2:5], off nt
	s_waitcnt lgkmcnt(0)

; #define LAS __attribute__((address_space(3)))
; #define LDS_WAIT() asm volatile("s_waitcnt lgkmcnt(0)" ::: "memory")
; __device__ __forceinline__ unsigned pk2(float lo, float hi) { return pg8::cvt_pk_bf16(lo, hi); }
; __device__ __forceinline__ void transpose_item(const float* W, int K, int N, bf16_t* WT, int mode, const float* kscale, LAS float* scr, int item, int lane) {
;     const int nblk = N / 32, kb = item / nblk, nb = item % nblk, k0 = 64 * kb, n0 = 32 * nb;
;     const int drow = (mode == 0 || mode == 3) ? n0 : ((n0 >> 7) * 256 + (n0 & 127) + (mode == 2 ? 128 : 0));
;     f32x4 t[8];
; #pragma unroll
;     for (int i = 0; i < 8; ++i) t[i] = *(const f32x4*)(W + (size_t)(k0 + 8 * i + (lane >> 3)) * N + n0 + 4 * (lane & 7));
; #pragma unroll
;     for (int i = 0; i < 8; ++i) { const int kk = 8 * i + (lane >> 3); const float sc = kscale ? kscale[k0 + kk] : 1.f; LAS float* d = scr + kk * 33 + 4 * (lane & 7);
;         d[0] = t[i][0] * sc; d[1] = t[i][1] * sc; d[2] = t[i][2] * sc; d[3] = t[i][3] * sc; }
;     LDS_WAIT(); asm volatile("" ::: "memory");
;     const int c = lane & 7;
; #pragma unroll
;     for (int j = 0; j < 4; ++j) { const int n = (lane >> 3) + 8 * j; const LAS float* s = scr + (8 * c) * 33 + n;
;         int dn = n;
;         if (mode == 3 && n0 >= 2048 && n0 < 6144) { const int d = (n0 & 127) + n; dn = ((d >> 4) & 3) * 32 + ((d >> 2) & 3) * 8 + (d >> 6) * 4 + (d & 3) - (n0 & 127); }
;         u32x4 o; o.x = pk2(s[0 * 33], s[1 * 33]); o.y = pk2(s[2 * 33], s[3 * 33]); o.z = pk2(s[4 * 33], s[5 * 33]); o.w = pk2(s[6 * 33], s[7 * 33]);
;         *(u32x4*)(WT + (size_t)(drow + dn) * K + k0 + 8 * c) = o; }
;     LDS_WAIT(); asm volatile("" ::: "memory");
; }
.LBB0_548:
	s_andn2_b64 vcc, exec, s[6:7]
	s_cbranch_vccnz .LBB0_550
	s_load_dwordx2 s[6:7], s[16:17], 0x58
	s_add_i32 s10, s22, 0xe400
	s_lshl_b64 s[8:9], s[18:19], 24
	v_lshlrev_b32_e32 v196, 2, v36
	v_add_u32_e32 v40, v39, v41
	s_waitcnt lgkmcnt(0)
	s_add_u32 s8, s6, s8
	s_addc_u32 s7, s7, s9
	s_and_b32 s6, s25, 0x7e0
	s_and_b32 s10, s10, 0xffc0
	s_lshl_b32 s9, s6, 2
	s_add_u32 s8, s8, s9
	v_or_b32_e32 v4, s10, v34
	s_addc_u32 s9, s7, 0
	v_lshl_add_u64 v[2:3], s[8:9], 0, v[196:197]
	v_lshlrev_b32_e32 v196, 13, v4
	v_lshl_add_u64 v[30:31], v[2:3], 0, v[196:197]
	s_mov_b32 s7, 0x10000
	v_add_co_u32_e32 v6, vcc, s7, v30
	s_mov_b32 s7, 0x20000
	s_nop 0
	v_addc_co_u32_e32 v7, vcc, 0, v31, vcc
	v_add_co_u32_e32 v10, vcc, s7, v30
	s_mov_b32 s7, 0x30000
	s_nop 0
	v_addc_co_u32_e32 v11, vcc, 0, v31, vcc
	v_add_co_u32_e32 v14, vcc, s7, v30
	s_mov_b32 s7, 0x40000
	s_nop 0
	v_addc_co_u32_e32 v15, vcc, 0, v31, vcc
	v_add_co_u32_e32 v18, vcc, s7, v30
	s_mov_b32 s7, 0x50000
	s_nop 0
	v_addc_co_u32_e32 v19, vcc, 0, v31, vcc
	v_add_co_u32_e32 v22, vcc, s7, v30
	global_load_dwordx4 v[2:5], v[30:31], off nt
	s_nop 0
	global_load_dwordx4 v[6:9], v[6:7], off nt
	v_addc_co_u32_e32 v23, vcc, 0, v31, vcc
	global_load_dwordx4 v[10:13], v[10:11], off nt
	s_nop 0
	global_load_dwordx4 v[14:17], v[14:15], off nt
	s_nop 0
	global_load_dwordx4 v[18:21], v[18:19], off nt
	s_nop 0
	global_load_dwordx4 v[22:25], v[22:23], off nt
	s_mov_b32 s7, 0x60000
	v_add_co_u32_e32 v26, vcc, s7, v30
	s_mov_b32 s7, 0x70000
	s_nop 0
	v_addc_co_u32_e32 v27, vcc, 0, v31, vcc
	global_load_dwordx4 v[26:29], v[26:27], off nt
	v_add_co_u32_e32 v30, vcc, s7, v30
	v_add_u32_e32 v42, 0x420, v40
	s_nop 0
	v_addc_co_u32_e32 v31, vcc, 0, v31, vcc
	global_load_dwordx4 v[30:33], v[30:31], off nt
	v_add_u32_e32 v43, 0x428, v40
	v_add_u32_e32 v44, 0x840, v40
	v_add_u32_e32 v54, 0x848, v40
	v_add_u32_e32 v55, 0xc60, v40
	v_add_u32_e32 v56, 0xc68, v40
	v_add_u32_e32 v57, 0x1080, v40
	v_add_u32_e32 v58, 0x1088, v40
	v_add_u32_e32 v59, 0x14a0, v40
	v_add_u32_e32 v60, 0x14a8, v40
	v_add_u32_e32 v61, 0x18c0, v40
	v_add_u32_e32 v62, 0x18c8, v40
	v_add_u32_e32 v63, 0x1ce0, v40
	v_add_u32_e32 v64, 0x1ce8, v40
	s_lshl_b32 s7, s10, 1
	s_add_u32 s8, s29, s7
	s_addc_u32 s9, s28, 0
	v_lshlrev_b32_e32 v196, 1, v38
	s_waitcnt vmcnt(0)
	ds_write2_b32 v40, v2, v3 offset1:1
	ds_write2_b32 v40, v4, v5 offset0:2 offset1:3
	ds_write2_b32 v42, v6, v7 offset1:1
	ds_write2_b32 v43, v8, v9 offset1:1
	ds_write2_b32 v44, v10, v11 offset1:1
	ds_write2_b32 v54, v12, v13 offset1:1
	ds_write2_b32 v55, v14, v15 offset1:1
	ds_write2_b32 v56, v16, v17 offset1:1
	ds_write2_b32 v57, v18, v19 offset1:1
	ds_write2_b32 v58, v20, v21 offset1:1
	ds_write2_b32 v59, v22, v23 offset1:1
	ds_write2_b32 v60, v24, v25 offset1:1
	ds_write2_b32 v61, v26, v27 offset1:1
	ds_write2_b32 v62, v28, v29 offset1:1
	ds_write2_b32 v63, v30, v31 offset1:1
	ds_write2_b32 v64, v32, v33 offset1:1
	s_waitcnt lgkmcnt(0)
	ds_read2_b32 v[2:3], v48 offset1:33
	s_waitcnt lgkmcnt(0)
	v_cvt_pk_bf16_f32 v2, v2, v3
	ds_read2_b32 v[4:5], v48 offset0:66 offset1:99
	v_or_b32_e32 v10, s6, v34
	v_lshl_add_u64 v[8:9], s[8:9], 0, v[196:197]
	s_mov_b64 s[8:9], 0x1c00000
	s_waitcnt lgkmcnt(0)
	v_cvt_pk_bf16_f32 v3, v4, v5
	ds_read2_b32 v[4:5], v48 offset0:132 offset1:165
	v_lshlrev_b32_e32 v196, 12, v10
	v_lshl_add_u64 v[8:9], v[8:9], 0, s[8:9]
	s_waitcnt lgkmcnt(0)
	v_cvt_pk_bf16_f32 v4, v4, v5
	ds_read2_b32 v[6:7], v48 offset0:198 offset1:231
	s_waitcnt lgkmcnt(0)
	v_cvt_pk_bf16_f32 v5, v6, v7
	v_lshl_add_u64 v[10:11], v[8:9], 0, v[196:197]
	ds_read2_b32 v[6:7], v48 offset0:8 offset1:41
	global_store_dwordx4 v[10:11], v[2:5], off nt
	v_or_b32_e32 v10, s6, v45
	v_lshlrev_b32_e32 v196, 12, v10
	s_waitcnt lgkmcnt(0)
	v_cvt_pk_bf16_f32 v2, v6, v7
	ds_read2_b32 v[4:5], v48 offset0:74 offset1:107
	s_waitcnt lgkmcnt(0)
	v_cvt_pk_bf16_f32 v3, v4, v5
	ds_read2_b32 v[4:5], v48 offset0:140 offset1:173
	s_waitcnt lgkmcnt(0)
	v_cvt_pk_bf16_f32 v4, v4, v5
	ds_read2_b32 v[6:7], v48 offset0:206 offset1:239
	s_waitcnt lgkmcnt(0)
	v_cvt_pk_bf16_f32 v5, v6, v7
	v_lshl_add_u64 v[10:11], v[8:9], 0, v[196:197]
	ds_read2_b32 v[6:7], v48 offset0:16 offset1:49
	global_store_dwordx4 v[10:11], v[2:5], off nt
	v_or_b32_e32 v10, s6, v46
	v_lshlrev_b32_e32 v196, 12, v10
	s_waitcnt lgkmcnt(0)
	v_cvt_pk_bf16_f32 v2, v6, v7
	ds_read2_b32 v[4:5], v48 offset0:82 offset1:115
	s_waitcnt lgkmcnt(0)
	v_cvt_pk_bf16_f32 v3, v4, v5
	ds_read2_b32 v[4:5], v48 offset0:148 offset1:181
	s_waitcnt lgkmcnt(0)
	v_cvt_pk_bf16_f32 v4, v4, v5
	ds_read2_b32 v[6:7], v48 offset0:214 offset1:247
	s_waitcnt lgkmcnt(0)
	v_cvt_pk_bf16_f32 v5, v6, v7
	v_lshl_add_u64 v[10:11], v[8:9], 0, v[196:197]
	ds_read2_b32 v[6:7], v48 offset0:24 offset1:57
	global_store_dwordx4 v[10:11], v[2:5], off nt
	s_waitcnt lgkmcnt(0)
	s_nop 0
	v_cvt_pk_bf16_f32 v2, v6, v7
	ds_read2_b32 v[4:5], v48 offset0:90 offset1:123
	s_waitcnt lgkmcnt(0)
	v_cvt_pk_bf16_f32 v3, v4, v5
	ds_read2_b32 v[4:5], v48 offset0:156 offset1:189
	s_waitcnt lgkmcnt(0)
	v_cvt_pk_bf16_f32 v4, v4, v5
	v_or_b32_e32 v5, s6, v47
	ds_read2_b32 v[6:7], v48 offset0:222 offset1:255
	v_lshlrev_b32_e32 v196, 12, v5
	s_waitcnt lgkmcnt(0)
	v_cvt_pk_bf16_f32 v5, v6, v7
	v_lshl_add_u64 v[6:7], v[8:9], 0, v[196:197]
	global_store_dwordx4 v[6:7], v[2:5], off nt
	s_waitcnt lgkmcnt(0)

; __device__ __forceinline__ unsigned pk2(float lo, float hi) { return pg8::cvt_pk_bf16(lo, hi); }
; __device__ __forceinline__ void convert_rows(const float* X, bf16_t* out, float* rsq, int gw, int ngw, int lane) {
;     ...
;         u32x2* o8 = (u32x2*)(out + (size_t)m * DM) + lane;
; #pragma unroll
;         for (int j = 0; j < 8; ++j) { u32x2 w; w.x = pk2(v[j].x, v[j].y); w.y = pk2(v[j].z, v[j].w); o8[64 * j] = w; }
;     }
.LBB0_568:
	s_or_b64 exec, exec, s[18:19]
	s_waitcnt lgkmcnt(0)
	v_lshl_add_u64 v[44:45], s[0:1], 0, v[36:37]
	v_cvt_pk_bf16_f32 v30, v30, v31
	v_cvt_pk_bf16_f32 v31, v32, v33
	v_add_co_u32_e32 v32, vcc, 0xd400000, v44
	s_add_i32 s12, s12, s14
	s_nop 0
	v_addc_co_u32_e32 v33, vcc, 0, v45, vcc
	global_store_dwordx2 v[32:33], v[30:31], off nt
	v_cvt_pk_bf16_f32 v2, v2, v3
	v_cvt_pk_bf16_f32 v3, v4, v5
	global_store_dwordx2 v[32:33], v[2:3], off offset:512 nt
	v_cvt_pk_bf16_f32 v2, v6, v7
	v_cvt_pk_bf16_f32 v3, v8, v9
	global_store_dwordx2 v[32:33], v[2:3], off offset:1024 nt
	v_cvt_pk_bf16_f32 v2, v10, v11
	v_cvt_pk_bf16_f32 v3, v12, v13
	global_store_dwordx2 v[32:33], v[2:3], off offset:1536 nt
	v_cvt_pk_bf16_f32 v2, v14, v15
	v_cvt_pk_bf16_f32 v3, v16, v17
	s_add_u32 s20, s20, s8
	global_store_dwordx2 v[32:33], v[2:3], off offset:2048 nt
	v_cvt_pk_bf16_f32 v2, v18, v19
	v_cvt_pk_bf16_f32 v3, v20, v21
	s_addc_u32 s21, s21, s9
	global_store_dwordx2 v[32:33], v[2:3], off offset:2560 nt
	v_cvt_pk_bf16_f32 v2, v22, v23
	v_cvt_pk_bf16_f32 v3, v24, v25
	v_lshl_add_u64 v[34:35], v[34:35], 0, s[10:11]
	s_cmpk_gt_i32 s12, 0x3fff
	v_lshl_add_u64 v[36:37], v[36:37], 0, s[16:17]
	global_store_dwordx2 v[32:33], v[2:3], off offset:3072 nt
	v_cvt_pk_bf16_f32 v2, v26, v27
	v_cvt_pk_bf16_f32 v3, v28, v29
	global_store_dwordx2 v[32:33], v[2:3], off offset:3584 nt
	s_cbranch_scc1 .LBB0_571
